# v098 + attention: scan/ssm workgroups draw their first item from the XCD work counter (only the ten role-free workgroups per XCD keep a static first item), so a late role workgroup owes no reserved it
# speedup vs baseline: 1.0090x; 1.0090x over previous
; #define LAS __attribute__((address_space(3)))
; __device__ __forceinline__ float xsum32(float v) { auto r = __builtin_amdgcn_permlane32_swap(__float_as_uint(v), __float_as_uint(v), false, false); return __uint_as_float(r[0]) + __uint_as_float(r[1]); }
; __device__ __forceinline__ int crow16(int g, int hh) { return (g & 3) + 8 * (g >> 2) + 4 * hh; }
; __device__ __forceinline__ void attn_v2(const KA& A, const Ctx& F, int l) {
;     ...
;     const int lane = F.lane, q = lane & 31, hh = lane >> 5, w = F.wave;
;     unsigned* ctr = (unsigned*)(F.ws + WS_CTL) + CW_ATT + 64 * l + ((F.dry && (DRY_SEL & 2)) ? 32 : 0); volatile LAS unsigned* slot = (volatile LAS unsigned*)(F.lds + MISC_OFF + 64);
;     bool first_ = true;
; #pragma unroll 1
;     for (;;) {
;         int item;
;         if (first_) { item = F.bid; first_ = false; }
;         else { if (F.tid == 0) *slot = 256u + __hip_atomic_fetch_add(ctr, 1u, __ATOMIC_RELAXED, __HIP_MEMORY_SCOPE_AGENT);
;                __syncthreads();
;                item = (int)*slot; }
;         if (item >= ATT_ITEMS) break;
;         const int idx16 = item & 15, h = (item >> 4) % 6, b = item / 96;
;     ...
;         const int kbase = i0 + 32 * w - 128;
;         float mx = -3.0e38f;
; #pragma unroll
;         for (int kt = 0; kt < 5; ++kt) {
;             if (kt == 0 || kt == 4 || kbase < 0) {
; #pragma unroll
;                 for (int gq = 0; gq < 16; ++gq) { const int kl = crow16(gq, hh); const int dist = q + 128 - 32 * kt - kl;
;                     const bool ok = (dist >= 0) && (dist <= 128) && (kbase + 32 * kt + kl >= 0);
;                     if (!ok) p[kt][gq] = -3.0e38f; } }
; #pragma unroll
;             for (int gq = 0; gq < 16; ++gq) mx = fmaxf(mx, p[kt][gq]);
;         }
;         mx = xmax32(mx);
;         const float sc = 0.125f * 1.4426950408889634f;
;         float l = 0.f;
; #pragma unroll
;         for (int kt = 0; kt < 5; ++kt)
; #pragma unroll
;             for (int gq = 0; gq < 16; ++gq) { const float e = __builtin_amdgcn_exp2f((p[kt][gq] - mx) * sc); p[kt][gq] = e; l += e; }
;         l = xsum32(l);
;         asm volatile("s_waitcnt lgkmcnt(0)" ::: "memory"); __builtin_amdgcn_s_barrier(); asm volatile("" ::: "memory");
;         f32x16 o[2]; o[0] = f32x16{}; o[1] = f32x16{};
;         const unsigned char* vb = VI + ((32 * w + 4 * hh + ((lane & 15) >> 2)) * ATT_VS + 16 * ((lane >> 4) & 1) + 4 * (lane & 3)) * 2;
.LBB0_197:
	s_lshl_b32 s2, s79, 6
	v_readlane_b32 s8, v253, 60
	s_ashr_i32 s3, s2, 31
	v_readlane_b32 s10, v253, 62
	v_mov_b32_e32 v1, v242
	v_readlane_b32 s11, v253, 63
	s_add_u32 s0, s10, 0x1a400000
	s_waitcnt vmcnt(0) lgkmcnt(0)
	s_barrier
	s_addc_u32 s1, s11, 0
	v_and_b32_e32 v142, 31, v1
	v_bfe_u32 v3, v1, 5, 1
	s_lshl_b64 s[2:3], s[2:3], 2
	v_and_b32_e32 v2, 63, v1
	s_add_u32 s2, s10, s2
	v_lshlrev_b32_e32 v0, 3, v3
	v_lshlrev_b32_e32 v143, 2, v3
	v_or_b32_e32 v3, 0x80, v142
	s_addc_u32 s3, s11, s3
	v_cmp_gt_u32_e64 s[38:39], 32, v2
	v_sub_u32_e32 v2, v3, v143
	s_movk_i32 s6, 0x81
	s_add_u32 s16, s2, 0x1000
	v_cmp_gt_u32_e64 s[40:41], s6, v2
	v_sub_u32_e32 v2, v143, v3
	s_movk_i32 s2, 0xff7e
	v_or_b32_e32 v144, 2, v143
	v_cmp_lt_u32_e64 s[42:43], s2, v2
	v_sub_u32_e32 v2, v3, v144
	v_or_b32_e32 v145, 3, v143
	v_cmp_gt_u32_e64 s[44:45], s6, v2
	v_sub_u32_e32 v2, v3, v145
	v_or_b32_e32 v146, 8, v143
	v_cmp_gt_u32_e64 s[46:47], s6, v2
	v_sub_u32_e32 v2, v3, v146
	v_or_b32_e32 v147, 9, v143
	v_cmp_gt_u32_e64 s[48:49], s6, v2
	v_sub_u32_e32 v2, v3, v147
	v_or_b32_e32 v148, 10, v143
	v_cmp_gt_u32_e64 s[50:51], s6, v2
	v_sub_u32_e32 v2, v3, v148
	v_or_b32_e32 v149, 11, v143
	v_cmp_gt_u32_e64 s[52:53], s6, v2
	v_sub_u32_e32 v2, v3, v149
	v_or_b32_e32 v150, 16, v143
	v_cmp_gt_u32_e64 s[54:55], s6, v2
	v_sub_u32_e32 v2, v3, v150
	v_or_b32_e32 v151, 17, v143
	v_cmp_gt_u32_e64 s[56:57], s6, v2
	v_sub_u32_e32 v2, v3, v151
	v_or_b32_e32 v152, 18, v143
	v_cmp_gt_u32_e64 s[58:59], s6, v2
	v_sub_u32_e32 v2, v3, v152
	v_or_b32_e32 v153, 19, v143
	v_cmp_gt_u32_e64 s[60:61], s6, v2
	v_sub_u32_e32 v2, v3, v153
	v_or_b32_e32 v154, 24, v143
	v_cmp_gt_u32_e64 s[62:63], s6, v2
	v_sub_u32_e32 v2, v3, v154
	v_or_b32_e32 v155, 25, v143
	v_cmp_gt_u32_e64 s[64:65], s6, v2
	v_sub_u32_e32 v2, v3, v155
	v_or_b32_e32 v156, 26, v143
	v_cmp_gt_u32_e64 s[66:67], s6, v2
	v_sub_u32_e32 v2, v3, v156
	v_or_b32_e32 v157, 27, v143
	v_cmp_gt_u32_e64 s[68:69], s6, v2
	v_sub_u32_e32 v2, v3, v157
	v_cmp_gt_u32_e64 s[70:71], s6, v2
	v_sub_u32_e32 v2, v142, v143
	v_sub_u32_e32 v3, v143, v142
	v_cmp_lt_u32_e64 s[74:75], s2, v3
	v_add_u32_e32 v3, -2, v2
	v_cmp_gt_u32_e64 s[76:77], s6, v3
	v_add_u32_e32 v3, -3, v2
	v_writelane_b32 v254, s79, 6
	v_cmp_gt_u32_e64 s[78:79], s6, v3
	v_add_u32_e32 v3, -8, v2
	v_cmp_gt_u32_e64 s[80:81], s6, v3
	v_add_u32_e32 v3, -9, v2
	v_cmp_gt_u32_e64 s[26:27], s6, v3
	v_add_u32_e32 v3, -10, v2
	v_cmp_gt_u32_e64 s[84:85], s6, v3
	v_add_u32_e32 v3, -11, v2
	v_cmp_gt_u32_e64 s[86:87], s6, v3
	v_add_u32_e32 v3, -16, v2
	v_cmp_gt_u32_e64 s[88:89], s6, v3
	v_subrev_u32_e32 v3, 17, v2
	v_readfirstlane_b32 s4, v1
	v_cmp_gt_u32_e64 s[90:91], s6, v3
	v_subrev_u32_e32 v3, 18, v2
	s_addc_u32 s17, s3, 0
	v_readlane_b32 s33, v253, 55
	s_nop 1
	s_and_b32 s13, s33, 7
	s_lshl_b32 s12, s13, 2
	s_add_u32 s16, s16, s12
	s_addc_u32 s17, s17, 0
	s_mulk_i32 s13, 0x60
	s_lshr_b32 s12, s33, 3
	s_add_i32 s12, s12, s13
	s_addk_i32 s12, 64
	s_nop 0
	v_writelane_b32 v255, s13, 48
	s_ashr_i32 s33, s4, 1
	v_cmp_gt_u32_e64 s[92:93], s6, v3
	v_subrev_u32_e32 v3, 19, v2
	s_andn2_b32 s33, s33, 31
	v_bfe_u32 v4, v1, 2, 2
	v_cmp_gt_u32_e64 s[94:95], s6, v3
	v_subrev_u32_e32 v3, 24, v2
	v_readlane_b32 s9, v253, 61
	v_or3_b32 v4, v4, v143, s33
	s_movk_i32 s10, 0x60
	v_lshlrev_b32_e32 v6, 2, v1
	v_cmp_gt_u32_e64 s[96:97], s6, v3
	v_subrev_u32_e32 v3, 25, v2
	v_mul_lo_u32 v4, v4, s10
	v_and_b32_e32 v5, 16, v1
	v_and_b32_e32 v6, 12, v6
	v_cmp_gt_u32_e64 s[72:73], s6, v2
	v_cmp_gt_u32_e64 s[2:3], s6, v3
	v_subrev_u32_e32 v3, 26, v2
	v_subrev_u32_e32 v2, 27, v2
	v_or_b32_e32 v173, 0xffffffe0, v1
	v_cmp_eq_u32_e64 s[8:9], 0, v1
	v_ashrrev_i32_e32 v174, 3, v1
	v_lshlrev_b32_e32 v1, 3, v1
	v_or3_b32 v4, v4, v5, v6
	v_cmp_gt_u32_e64 s[4:5], s6, v3
	v_cmp_gt_u32_e64 s[6:7], s6, v2
	v_and_b32_e32 v2, 56, v1
	v_mul_lo_u32 v1, v174, s10
	v_readlane_b32 s10, v253, 55
	s_nop 1
	v_lshlrev_b32_e32 v4, 1, v4
	v_add_lshl_u32 v1, v1, v2, 1
	v_writelane_b32 v255, s10, 38
	v_xor_b32_e32 v158, -9, v143
	v_xor_b32_e32 v159, -10, v143
	v_xor_b32_e32 v160, -11, v143
	v_xor_b32_e32 v161, -12, v143
	v_xor_b32_e32 v162, 0xffffffef, v143
	v_xor_b32_e32 v163, 0xffffffee, v143
	v_xor_b32_e32 v164, 0xffffffed, v143
	v_xor_b32_e32 v165, 0xffffffec, v143
	v_xor_b32_e32 v166, 0xffffffe7, v143
	v_xor_b32_e32 v167, 0xffffffe6, v143
	v_xor_b32_e32 v168, 0xffffffe5, v143
	v_xor_b32_e32 v169, 0xffffffe4, v143
	v_or_b32_e32 v170, 0xffffff80, v142
	v_or_b32_e32 v171, 0xffffffa0, v142
	v_or_b32_e32 v172, 0xffffffc0, v142
	v_add_u32_e32 v175, 0xffffff80, v174
	v_lshlrev_b32_e32 v134, 1, v2
	v_lshlrev_b32_e32 v136, 1, v0
	v_add_u32_e32 v176, 0, v1
	v_add_u32_e32 v177, 0, v4
	v_writelane_b32 v255, s11, 39
	v_readlane_b32 s10, v253, 55
	s_nop 1
	s_cmpk_gt_u32 s10, 0xaf
	s_cbranch_scc1 .LBB0_201
	s_mov_b64 exec, s[8:9]
	s_cbranch_execz .Latt_fc_skip
	v_mov_b32_e32 v178, 1
	s_nop 0
	global_atomic_add v178, v81, v178, s[16:17] sc0
	s_waitcnt vmcnt(0)
	v_readlane_b32 s12, v255, 48
	v_cmp_gt_u32_e32 vcc, 0x56, v178
	s_nop 0
	v_add_u32_e32 v0, s12, v178
	v_mov_b32_e32 v1, 0x300
	v_cndmask_b32_e32 v0, v1, v0, vcc
	v_readlane_b32 s12, v253, 50
	s_nop 1
	v_mov_b32_e32 v1, s12
	ds_write_b32 v1, v0
.Latt_fc_skip:
	s_mov_b64 exec, -1
	s_mov_b64 s[10:11], -1
	s_branch .LBB0_199
.LBB0_198:
	s_or_b64 exec, exec, s[12:13]
	s_nop 0
	v_readfirstlane_b32 s12, v1
	s_nop 1
	v_add_u32_e32 v0, s12, v0
	v_readlane_b32 s12, v255, 48
	v_cmp_gt_u32_e32 vcc, 0x56, v0
	s_nop 0
	v_add_u32_e32 v0, s12, v0
	v_mov_b32_e32 v1, 0x300
	v_cndmask_b32_e32 v0, v1, v0, vcc
	v_readlane_b32 s12, v253, 50
	s_nop 1
	v_mov_b32_e32 v1, s12
	ds_write_b32 v1, v0
